# v94: v91 + grid barrier issues the L1 invalidate before polling (overlaps the wait) instead of after the release
# speedup vs baseline: 1.0017x; 1.0017x over previous
; __device__ __forceinline__ unsigned xb_ld(unsigned* p)              { return __hip_atomic_load(p, __ATOMIC_RELAXED, __HIP_MEMORY_SCOPE_AGENT); }
; __device__ __forceinline__ unsigned xb_add(unsigned* p, unsigned v) { return __hip_atomic_fetch_add(p, v, __ATOMIC_RELAXED, __HIP_MEMORY_SCOPE_AGENT); }
; #define XB_SPIN(cond, bar) do { unsigned _sp = 0; while (cond) { __builtin_amdgcn_s_sleep(1); \
;     if ((++_sp & 255u) == 0u) { if (xb_ld(&(bar)[XB_TMO])) break; if (_sp > XB_SPIN_CAP) { atomicAdd(&(bar)[XB_TMO], 1u); break; } } } } while (0)
; __device__ __forceinline__ void xcd_barrier(const XcdBarrier& b) {
;     ...
;         const unsigned old = xb_add(&bar[XB_XSUB(b.x)], 1u);
;         const unsigned gen = old / nloc;
;         if (old + 1u == (gen + 1u) * nloc) {
;             __builtin_amdgcn_fence(__ATOMIC_RELEASE, "agent");
;             asm volatile("s_waitcnt vmcnt(0)" ::: "memory");
;             const unsigned og = xb_add(&bar[XB_TOP], 1u);
;             const unsigned tg = og / nx;
;             if (og + 1u == (tg + 1u) * nx) xb_add(&bar[XB_TOPGEN], 1u);
;             else XB_SPIN(xb_ld(&bar[XB_TOPGEN]) == tg, bar);
;             __builtin_amdgcn_fence(__ATOMIC_ACQUIRE, "agent");
;             xb_add(&bar[XB_XGEN(b.x)], 1u);
;             asm volatile("s_waitcnt vmcnt(0)" ::: "memory");
;         } else {
;             XB_SPIN(xb_ld(&bar[XB_XGEN(b.x)]) == gen, bar);
.LBB0_133:
	s_or_b64 exec, exec, s[10:11]
	v_cvt_f32_u32_e32 v5, v3
	s_waitcnt vmcnt(0)
	v_readfirstlane_b32 s0, v4
	v_sub_u32_e32 v4, 0, v3
	v_rcp_iflag_f32_e32 v5, v5
	v_add_u32_e32 v6, s0, v2
	v_mul_f32_e32 v5, 0x4f7ffffe, v5
	v_cvt_u32_f32_e32 v5, v5
	v_mul_lo_u32 v2, v4, v5
	v_mul_hi_u32 v2, v5, v2
	v_add_u32_e32 v2, v5, v2
	v_mul_hi_u32 v2, v6, v2
	v_mul_lo_u32 v4, v2, v3
	v_sub_u32_e32 v4, v6, v4
	v_add_u32_e32 v5, 1, v2
	v_cmp_ge_u32_e32 vcc, v4, v3
	s_nop 1
	v_cndmask_b32_e32 v2, v2, v5, vcc
	v_sub_u32_e32 v5, v4, v3
	v_cndmask_b32_e32 v4, v4, v5, vcc
	v_add_u32_e32 v5, 1, v2
	v_cmp_ge_u32_e32 vcc, v4, v3
	v_add_u32_e32 v4, 1, v6
	s_nop 0
	v_cndmask_b32_e32 v2, v2, v5, vcc
	v_mul_lo_u32 v5, v3, v2
	v_add_u32_e32 v3, v5, v3
	v_cmp_ne_u32_e32 vcc, v4, v3
	s_and_saveexec_b64 s[0:1], vcc
	s_xor_b64 s[8:9], exec, s[0:1]
	s_cbranch_execz .LBB0_147
	buffer_inv sc1
	s_waitcnt lgkmcnt(0)
	v_mov_b32_e32 v1, 0x2000
	global_load_dword v1, v1, s[6:7] offset:1024 sc1
	s_add_u32 s14, s6, 0x2400
	s_addc_u32 s15, s7, 0
	s_waitcnt vmcnt(0)
	v_cmp_eq_u32_e32 vcc, v1, v2
	s_and_saveexec_b64 s[10:11], vcc
	s_cbranch_execz .LBB0_146
	s_add_u32 s12, s4, 0x4200
	s_addc_u32 s13, s5, 0
	s_mov_b32 s0, 1
	s_mov_b64 s[16:17], 0
	v_mov_b32_e32 v1, 0
	s_branch .LBB0_137

; __device__ __forceinline__ unsigned xb_ld(unsigned* p)              { return __hip_atomic_load(p, __ATOMIC_RELAXED, __HIP_MEMORY_SCOPE_AGENT); }
; __device__ __forceinline__ unsigned xb_add(unsigned* p, unsigned v) { return __hip_atomic_fetch_add(p, v, __ATOMIC_RELAXED, __HIP_MEMORY_SCOPE_AGENT); }
; #define XB_SPIN(cond, bar) do { unsigned _sp = 0; while (cond) { __builtin_amdgcn_s_sleep(1); \
;     if ((++_sp & 255u) == 0u) { if (xb_ld(&(bar)[XB_TMO])) break; if (_sp > XB_SPIN_CAP) { atomicAdd(&(bar)[XB_TMO], 1u); break; } } } } while (0)
; __device__ __forceinline__ void xcd_barrier(const XcdBarrier& b) {
;     ...
;         if (old + 1u == (gen + 1u) * nloc) {
;             __builtin_amdgcn_fence(__ATOMIC_RELEASE, "agent");
;             asm volatile("s_waitcnt vmcnt(0)" ::: "memory");
;             const unsigned og = xb_add(&bar[XB_TOP], 1u);
;             const unsigned tg = og / nx;
;             if (og + 1u == (tg + 1u) * nx) xb_add(&bar[XB_TOPGEN], 1u);
;             else XB_SPIN(xb_ld(&bar[XB_TOPGEN]) == tg, bar);
;             __builtin_amdgcn_fence(__ATOMIC_ACQUIRE, "agent");
;             xb_add(&bar[XB_XGEN(b.x)], 1u);
;             asm volatile("s_waitcnt vmcnt(0)" ::: "memory");
;         } else {
;             XB_SPIN(xb_ld(&bar[XB_XGEN(b.x)]) == gen, bar);
;             __builtin_amdgcn_fence(__ATOMIC_ACQUIRE, "agent");
;             asm volatile("s_waitcnt vmcnt(0)" ::: "memory");
.LBB0_146:
	s_or_b64 exec, exec, s[10:11]
	s_waitcnt vmcnt(0)
	s_waitcnt vmcnt(0)
.LBB0_147:
	s_andn2_saveexec_b64 s[0:1], s[8:9]
	s_cbranch_execz .LBB0_167
	s_mov_b64 s[8:9], exec
	buffer_inv sc1
	buffer_wbl2 sc1
	s_waitcnt lgkmcnt(0)
	s_waitcnt vmcnt(0)
	v_mbcnt_lo_u32_b32 v2, s8, 0
	v_mbcnt_hi_u32_b32 v2, s9, v2
	v_cmp_eq_u32_e32 vcc, 0, v2
	s_and_saveexec_b64 s[10:11], vcc
	s_cbranch_execz .LBB0_150
	s_bcnt1_i32_b64 s0, s[8:9]
	v_mov_b32_e32 v3, 0x7000
	v_mov_b32_e32 v4, s0
	global_atomic_add v3, v3, v4, s[4:5] offset:1024 sc0

; __device__ __forceinline__ unsigned xb_add(unsigned* p, unsigned v) { return __hip_atomic_fetch_add(p, v, __ATOMIC_RELAXED, __HIP_MEMORY_SCOPE_AGENT); }
; __device__ __forceinline__ void xcd_barrier(const XcdBarrier& b) {
;     ...
;             __builtin_amdgcn_fence(__ATOMIC_ACQUIRE, "agent");
;             xb_add(&bar[XB_XGEN(b.x)], 1u);
;             asm volatile("s_waitcnt vmcnt(0)" ::: "memory");
.LBB0_164:
	s_or_b64 exec, exec, s[4:5]
	s_mov_b64 s[4:5], exec
	v_mbcnt_lo_u32_b32 v1, s4, 0
	v_mbcnt_hi_u32_b32 v1, s5, v1
	v_cmp_eq_u32_e32 vcc, 0, v1
	s_waitcnt vmcnt(0)
	s_and_saveexec_b64 s[8:9], vcc
	s_cbranch_execz .LBB0_166
	s_bcnt1_i32_b64 s0, s[4:5]
	v_mov_b32_e32 v1, 0x2000
	v_mov_b32_e32 v2, s0
	global_atomic_add v1, v2, s[6:7] offset:1024

; __device__ __forceinline__ unsigned xb_ld(unsigned* p)              { return __hip_atomic_load(p, __ATOMIC_RELAXED, __HIP_MEMORY_SCOPE_AGENT); }
; __device__ __forceinline__ unsigned xb_add(unsigned* p, unsigned v) { return __hip_atomic_fetch_add(p, v, __ATOMIC_RELAXED, __HIP_MEMORY_SCOPE_AGENT); }
; #define XB_SPIN(cond, bar) do { unsigned _sp = 0; while (cond) { __builtin_amdgcn_s_sleep(1); \
;     if ((++_sp & 255u) == 0u) { if (xb_ld(&(bar)[XB_TMO])) break; if (_sp > XB_SPIN_CAP) { atomicAdd(&(bar)[XB_TMO], 1u); break; } } } } while (0)
; __device__ __forceinline__ void xcd_barrier(const XcdBarrier& b) {
;     ...
;         const unsigned old = xb_add(&bar[XB_XSUB(b.x)], 1u);
;         const unsigned gen = old / nloc;
;         if (old + 1u == (gen + 1u) * nloc) {
;             __builtin_amdgcn_fence(__ATOMIC_RELEASE, "agent");
;             asm volatile("s_waitcnt vmcnt(0)" ::: "memory");
;             const unsigned og = xb_add(&bar[XB_TOP], 1u);
;             const unsigned tg = og / nx;
;             if (og + 1u == (tg + 1u) * nx) xb_add(&bar[XB_TOPGEN], 1u);
;             else XB_SPIN(xb_ld(&bar[XB_TOPGEN]) == tg, bar);
;             __builtin_amdgcn_fence(__ATOMIC_ACQUIRE, "agent");
;             xb_add(&bar[XB_XGEN(b.x)], 1u);
;             asm volatile("s_waitcnt vmcnt(0)" ::: "memory");
;         } else {
;             XB_SPIN(xb_ld(&bar[XB_XGEN(b.x)]) == gen, bar);
.LBB0_319:
	s_or_b64 exec, exec, s[14:15]
	v_cvt_f32_u32_e32 v6, v4
	s_waitcnt vmcnt(0)
	v_readfirstlane_b32 s1, v5
	v_sub_u32_e32 v5, 0, v4
	v_rcp_iflag_f32_e32 v6, v6
	v_add_u32_e32 v7, s1, v3
	v_mul_f32_e32 v6, 0x4f7ffffe, v6
	v_cvt_u32_f32_e32 v6, v6
	v_mul_lo_u32 v3, v5, v6
	v_mul_hi_u32 v3, v6, v3
	v_add_u32_e32 v3, v6, v3
	v_mul_hi_u32 v3, v7, v3
	v_mul_lo_u32 v5, v3, v4
	v_sub_u32_e32 v5, v7, v5
	v_add_u32_e32 v6, 1, v3
	v_cmp_ge_u32_e32 vcc, v5, v4
	s_nop 1
	v_cndmask_b32_e32 v3, v3, v6, vcc
	v_sub_u32_e32 v6, v5, v4
	v_cndmask_b32_e32 v5, v5, v6, vcc
	v_add_u32_e32 v6, 1, v3
	v_cmp_ge_u32_e32 vcc, v5, v4
	v_add_u32_e32 v5, 1, v7
	s_nop 0
	v_cndmask_b32_e32 v3, v3, v6, vcc
	v_mul_lo_u32 v6, v4, v3
	v_add_u32_e32 v4, v6, v4
	v_cmp_ne_u32_e32 vcc, v5, v4
	s_and_saveexec_b64 s[2:3], vcc
	s_xor_b64 s[10:11], exec, s[2:3]
	s_cbranch_execz .LBB0_333
	buffer_inv sc1
	s_waitcnt lgkmcnt(0)
	v_mov_b32_e32 v2, 0x2000
	global_load_dword v2, v2, s[8:9] offset:1024 sc1
	s_add_u32 s18, s8, 0x2400
	s_addc_u32 s19, s9, 0
	s_waitcnt vmcnt(0)
	v_cmp_eq_u32_e32 vcc, v2, v3
	s_and_saveexec_b64 s[14:15], vcc
	s_cbranch_execz .LBB0_332
	s_add_u32 s16, s6, 0x4200
	s_addc_u32 s17, s7, 0
	s_mov_b32 s1, 1
	s_mov_b64 s[20:21], 0
	s_branch .LBB0_323

; __device__ __forceinline__ unsigned xb_ld(unsigned* p)              { return __hip_atomic_load(p, __ATOMIC_RELAXED, __HIP_MEMORY_SCOPE_AGENT); }
; __device__ __forceinline__ unsigned xb_add(unsigned* p, unsigned v) { return __hip_atomic_fetch_add(p, v, __ATOMIC_RELAXED, __HIP_MEMORY_SCOPE_AGENT); }
; #define XB_SPIN(cond, bar) do { unsigned _sp = 0; while (cond) { __builtin_amdgcn_s_sleep(1); \
;     if ((++_sp & 255u) == 0u) { if (xb_ld(&(bar)[XB_TMO])) break; if (_sp > XB_SPIN_CAP) { atomicAdd(&(bar)[XB_TMO], 1u); break; } } } } while (0)
; __device__ __forceinline__ void xcd_barrier(const XcdBarrier& b) {
;     ...
;         if (old + 1u == (gen + 1u) * nloc) {
;             __builtin_amdgcn_fence(__ATOMIC_RELEASE, "agent");
;             asm volatile("s_waitcnt vmcnt(0)" ::: "memory");
;             const unsigned og = xb_add(&bar[XB_TOP], 1u);
;             const unsigned tg = og / nx;
;             if (og + 1u == (tg + 1u) * nx) xb_add(&bar[XB_TOPGEN], 1u);
;             else XB_SPIN(xb_ld(&bar[XB_TOPGEN]) == tg, bar);
;             __builtin_amdgcn_fence(__ATOMIC_ACQUIRE, "agent");
;             xb_add(&bar[XB_XGEN(b.x)], 1u);
;             asm volatile("s_waitcnt vmcnt(0)" ::: "memory");
;         } else {
;             XB_SPIN(xb_ld(&bar[XB_XGEN(b.x)]) == gen, bar);
;             __builtin_amdgcn_fence(__ATOMIC_ACQUIRE, "agent");
;             asm volatile("s_waitcnt vmcnt(0)" ::: "memory");
.LBB0_332:
	s_or_b64 exec, exec, s[14:15]
	s_waitcnt vmcnt(0)
	s_waitcnt vmcnt(0)
.LBB0_333:
	s_andn2_saveexec_b64 s[2:3], s[10:11]
	s_cbranch_execz .LBB0_353
	s_mov_b64 s[10:11], exec
	buffer_inv sc1
	buffer_wbl2 sc1
	s_waitcnt lgkmcnt(0)
	s_waitcnt vmcnt(0)
	v_mbcnt_lo_u32_b32 v3, s10, 0
	v_mbcnt_hi_u32_b32 v3, s11, v3
	v_cmp_eq_u32_e32 vcc, 0, v3
	s_and_saveexec_b64 s[14:15], vcc
	s_cbranch_execz .LBB0_336
	s_bcnt1_i32_b64 s1, s[10:11]
	v_mov_b32_e32 v4, s1
	v_mov_b32_e32 v5, 0x7000
	global_atomic_add v4, v5, v4, s[6:7] offset:1024 sc0

; __device__ __forceinline__ unsigned xb_add(unsigned* p, unsigned v) { return __hip_atomic_fetch_add(p, v, __ATOMIC_RELAXED, __HIP_MEMORY_SCOPE_AGENT); }
; __device__ __forceinline__ void xcd_barrier(const XcdBarrier& b) {
;     ...
;             __builtin_amdgcn_fence(__ATOMIC_ACQUIRE, "agent");
;             xb_add(&bar[XB_XGEN(b.x)], 1u);
;             asm volatile("s_waitcnt vmcnt(0)" ::: "memory");
.LBB0_350:
	s_or_b64 exec, exec, s[6:7]
	s_mov_b64 s[6:7], exec
	v_mbcnt_lo_u32_b32 v2, s6, 0
	v_mbcnt_hi_u32_b32 v2, s7, v2
	v_cmp_eq_u32_e32 vcc, 0, v2
	s_waitcnt vmcnt(0)
	s_and_saveexec_b64 s[10:11], vcc
	s_cbranch_execz .LBB0_352
	s_bcnt1_i32_b64 s1, s[6:7]
	v_mov_b32_e32 v2, s1
	v_mov_b32_e32 v3, 0x2000
	global_atomic_add v3, v2, s[8:9] offset:1024

; __device__ __forceinline__ unsigned xb_ld(unsigned* p)              { return __hip_atomic_load(p, __ATOMIC_RELAXED, __HIP_MEMORY_SCOPE_AGENT); }
; __device__ __forceinline__ unsigned xb_add(unsigned* p, unsigned v) { return __hip_atomic_fetch_add(p, v, __ATOMIC_RELAXED, __HIP_MEMORY_SCOPE_AGENT); }
; #define XB_SPIN(cond, bar) do { unsigned _sp = 0; while (cond) { __builtin_amdgcn_s_sleep(1); \
;     if ((++_sp & 255u) == 0u) { if (xb_ld(&(bar)[XB_TMO])) break; if (_sp > XB_SPIN_CAP) { atomicAdd(&(bar)[XB_TMO], 1u); break; } } } } while (0)
; __device__ __forceinline__ void xcd_barrier(const XcdBarrier& b) {
;     ...
;         const unsigned old = xb_add(&bar[XB_XSUB(b.x)], 1u);
;         const unsigned gen = old / nloc;
;         if (old + 1u == (gen + 1u) * nloc) {
;             __builtin_amdgcn_fence(__ATOMIC_RELEASE, "agent");
;             asm volatile("s_waitcnt vmcnt(0)" ::: "memory");
;             const unsigned og = xb_add(&bar[XB_TOP], 1u);
;             const unsigned tg = og / nx;
;             if (og + 1u == (tg + 1u) * nx) xb_add(&bar[XB_TOPGEN], 1u);
;             else XB_SPIN(xb_ld(&bar[XB_TOPGEN]) == tg, bar);
;             __builtin_amdgcn_fence(__ATOMIC_ACQUIRE, "agent");
;             xb_add(&bar[XB_XGEN(b.x)], 1u);
;             asm volatile("s_waitcnt vmcnt(0)" ::: "memory");
;         } else {
;             XB_SPIN(xb_ld(&bar[XB_XGEN(b.x)]) == gen, bar);
.LBB0_450:
	s_or_b64 exec, exec, s[12:13]
	v_cvt_f32_u32_e32 v6, v4
	s_waitcnt vmcnt(0)
	v_readfirstlane_b32 s1, v5
	v_sub_u32_e32 v5, 0, v4
	v_rcp_iflag_f32_e32 v6, v6
	v_add_u32_e32 v7, s1, v3
	v_mul_f32_e32 v6, 0x4f7ffffe, v6
	v_cvt_u32_f32_e32 v6, v6
	v_mul_lo_u32 v3, v5, v6
	v_mul_hi_u32 v3, v6, v3
	v_add_u32_e32 v3, v6, v3
	v_mul_hi_u32 v3, v7, v3
	v_mul_lo_u32 v5, v3, v4
	v_sub_u32_e32 v5, v7, v5
	v_add_u32_e32 v6, 1, v3
	v_cmp_ge_u32_e32 vcc, v5, v4
	s_nop 1
	v_cndmask_b32_e32 v3, v3, v6, vcc
	v_sub_u32_e32 v6, v5, v4
	v_cndmask_b32_e32 v5, v5, v6, vcc
	v_add_u32_e32 v6, 1, v3
	v_cmp_ge_u32_e32 vcc, v5, v4
	v_add_u32_e32 v5, 1, v7
	s_nop 0
	v_cndmask_b32_e32 v3, v3, v6, vcc
	v_mul_lo_u32 v6, v4, v3
	v_add_u32_e32 v4, v6, v4
	v_cmp_ne_u32_e32 vcc, v5, v4
	s_and_saveexec_b64 s[2:3], vcc
	s_xor_b64 s[10:11], exec, s[2:3]
	s_cbranch_execz .LBB0_464
	buffer_inv sc1
	s_waitcnt lgkmcnt(0)
	v_mov_b32_e32 v2, 0x2000
	global_load_dword v2, v2, s[8:9] offset:1024 sc1
	s_add_u32 s16, s8, 0x2400
	s_addc_u32 s17, s9, 0
	s_waitcnt vmcnt(0)
	v_cmp_eq_u32_e32 vcc, v2, v3
	s_and_saveexec_b64 s[12:13], vcc
	s_cbranch_execz .LBB0_463
	s_add_u32 s14, s6, 0x4200
	s_addc_u32 s15, s7, 0
	s_mov_b32 s1, 1
	s_mov_b64 s[18:19], 0
	s_branch .LBB0_454

; __device__ __forceinline__ unsigned xb_ld(unsigned* p)              { return __hip_atomic_load(p, __ATOMIC_RELAXED, __HIP_MEMORY_SCOPE_AGENT); }
; __device__ __forceinline__ unsigned xb_add(unsigned* p, unsigned v) { return __hip_atomic_fetch_add(p, v, __ATOMIC_RELAXED, __HIP_MEMORY_SCOPE_AGENT); }
; #define XB_SPIN(cond, bar) do { unsigned _sp = 0; while (cond) { __builtin_amdgcn_s_sleep(1); \
;     if ((++_sp & 255u) == 0u) { if (xb_ld(&(bar)[XB_TMO])) break; if (_sp > XB_SPIN_CAP) { atomicAdd(&(bar)[XB_TMO], 1u); break; } } } } while (0)
; __device__ __forceinline__ void xcd_barrier(const XcdBarrier& b) {
;     ...
;         if (old + 1u == (gen + 1u) * nloc) {
;             __builtin_amdgcn_fence(__ATOMIC_RELEASE, "agent");
;             asm volatile("s_waitcnt vmcnt(0)" ::: "memory");
;             const unsigned og = xb_add(&bar[XB_TOP], 1u);
;             const unsigned tg = og / nx;
;             if (og + 1u == (tg + 1u) * nx) xb_add(&bar[XB_TOPGEN], 1u);
;             else XB_SPIN(xb_ld(&bar[XB_TOPGEN]) == tg, bar);
;             __builtin_amdgcn_fence(__ATOMIC_ACQUIRE, "agent");
;             xb_add(&bar[XB_XGEN(b.x)], 1u);
;             asm volatile("s_waitcnt vmcnt(0)" ::: "memory");
;         } else {
;             XB_SPIN(xb_ld(&bar[XB_XGEN(b.x)]) == gen, bar);
;             __builtin_amdgcn_fence(__ATOMIC_ACQUIRE, "agent");
;             asm volatile("s_waitcnt vmcnt(0)" ::: "memory");
.LBB0_463:
	s_or_b64 exec, exec, s[12:13]
	s_waitcnt vmcnt(0)
	s_waitcnt vmcnt(0)
.LBB0_464:
	s_andn2_saveexec_b64 s[2:3], s[10:11]
	s_cbranch_execz .LBB0_484
	s_mov_b64 s[10:11], exec
	buffer_inv sc1
	buffer_wbl2 sc1
	s_waitcnt lgkmcnt(0)
	s_waitcnt vmcnt(0)
	v_mbcnt_lo_u32_b32 v3, s10, 0
	v_mbcnt_hi_u32_b32 v3, s11, v3
	v_cmp_eq_u32_e32 vcc, 0, v3
	s_and_saveexec_b64 s[12:13], vcc
	s_cbranch_execz .LBB0_467
	s_bcnt1_i32_b64 s1, s[10:11]
	v_mov_b32_e32 v4, s1
	v_mov_b32_e32 v5, 0x7000
	global_atomic_add v4, v5, v4, s[6:7] offset:1024 sc0

; __device__ __forceinline__ unsigned xb_ld(unsigned* p)              { return __hip_atomic_load(p, __ATOMIC_RELAXED, __HIP_MEMORY_SCOPE_AGENT); }
; __device__ __forceinline__ unsigned xb_add(unsigned* p, unsigned v) { return __hip_atomic_fetch_add(p, v, __ATOMIC_RELAXED, __HIP_MEMORY_SCOPE_AGENT); }
; #define XB_SPIN(cond, bar) do { unsigned _sp = 0; while (cond) { __builtin_amdgcn_s_sleep(1); \
;     if ((++_sp & 255u) == 0u) { if (xb_ld(&(bar)[XB_TMO])) break; if (_sp > XB_SPIN_CAP) { atomicAdd(&(bar)[XB_TMO], 1u); break; } } } } while (0)
; __device__ __forceinline__ void xcd_barrier(const XcdBarrier& b) {
;     ...
;         const unsigned old = xb_add(&bar[XB_XSUB(b.x)], 1u);
;         const unsigned gen = old / nloc;
;         if (old + 1u == (gen + 1u) * nloc) {
;             __builtin_amdgcn_fence(__ATOMIC_RELEASE, "agent");
;             asm volatile("s_waitcnt vmcnt(0)" ::: "memory");
;             const unsigned og = xb_add(&bar[XB_TOP], 1u);
;             const unsigned tg = og / nx;
;             if (og + 1u == (tg + 1u) * nx) xb_add(&bar[XB_TOPGEN], 1u);
;             else XB_SPIN(xb_ld(&bar[XB_TOPGEN]) == tg, bar);
;             __builtin_amdgcn_fence(__ATOMIC_ACQUIRE, "agent");
;             xb_add(&bar[XB_XGEN(b.x)], 1u);
;             asm volatile("s_waitcnt vmcnt(0)" ::: "memory");
;         } else {
;             XB_SPIN(xb_ld(&bar[XB_XGEN(b.x)]) == gen, bar);
.LBB0_520:
	s_or_b64 exec, exec, s[12:13]
	v_cvt_f32_u32_e32 v6, v4
	s_waitcnt vmcnt(0)
	v_readfirstlane_b32 s0, v5
	v_sub_u32_e32 v5, 0, v4
	v_rcp_iflag_f32_e32 v6, v6
	v_add_u32_e32 v7, s0, v3
	v_mul_f32_e32 v6, 0x4f7ffffe, v6
	v_cvt_u32_f32_e32 v6, v6
	v_mul_lo_u32 v3, v5, v6
	v_mul_hi_u32 v3, v6, v3
	v_add_u32_e32 v3, v6, v3
	v_mul_hi_u32 v3, v7, v3
	v_mul_lo_u32 v5, v3, v4
	v_sub_u32_e32 v5, v7, v5
	v_add_u32_e32 v6, 1, v3
	v_cmp_ge_u32_e32 vcc, v5, v4
	s_nop 1
	v_cndmask_b32_e32 v3, v3, v6, vcc
	v_sub_u32_e32 v6, v5, v4
	v_cndmask_b32_e32 v5, v5, v6, vcc
	v_add_u32_e32 v6, 1, v3
	v_cmp_ge_u32_e32 vcc, v5, v4
	v_add_u32_e32 v5, 1, v7
	s_nop 0
	v_cndmask_b32_e32 v3, v3, v6, vcc
	v_mul_lo_u32 v6, v4, v3
	v_add_u32_e32 v4, v6, v4
	v_cmp_ne_u32_e32 vcc, v5, v4
	s_and_saveexec_b64 s[2:3], vcc
	s_xor_b64 s[10:11], exec, s[2:3]
	s_cbranch_execz .LBB0_534
	buffer_inv sc1
	s_waitcnt lgkmcnt(0)
	v_mov_b32_e32 v2, 0x2000
	global_load_dword v2, v2, s[8:9] offset:1024 sc1
	s_add_u32 s16, s8, 0x2400
	s_addc_u32 s17, s9, 0
	s_waitcnt vmcnt(0)
	v_cmp_eq_u32_e32 vcc, v2, v3
	s_and_saveexec_b64 s[12:13], vcc
	s_cbranch_execz .LBB0_533
	s_add_u32 s14, s6, 0x4200
	s_addc_u32 s15, s7, 0
	s_mov_b32 s0, 1
	s_mov_b64 s[18:19], 0
	s_branch .LBB0_524

; __device__ __forceinline__ unsigned xb_add(unsigned* p, unsigned v) { return __hip_atomic_fetch_add(p, v, __ATOMIC_RELAXED, __HIP_MEMORY_SCOPE_AGENT); }
; __device__ __forceinline__ void xcd_barrier(const XcdBarrier& b) {
;     ...
;         if (old + 1u == (gen + 1u) * nloc) {
;             __builtin_amdgcn_fence(__ATOMIC_RELEASE, "agent");
;             asm volatile("s_waitcnt vmcnt(0)" ::: "memory");
;             const unsigned og = xb_add(&bar[XB_TOP], 1u);
.LBB0_534:
	s_andn2_saveexec_b64 s[2:3], s[10:11]
	s_cbranch_execz .LBB0_554
	s_mov_b64 s[10:11], exec
	buffer_inv sc1
	buffer_wbl2 sc1
	s_waitcnt lgkmcnt(0)
	s_waitcnt vmcnt(0)
	v_mbcnt_lo_u32_b32 v3, s10, 0
	v_mbcnt_hi_u32_b32 v3, s11, v3
	v_cmp_eq_u32_e32 vcc, 0, v3
	s_and_saveexec_b64 s[12:13], vcc
	s_cbranch_execz .LBB0_537
	s_bcnt1_i32_b64 s0, s[10:11]
	v_mov_b32_e32 v4, s0
	v_mov_b32_e32 v5, 0x7000
	global_atomic_add v4, v5, v4, s[6:7] offset:1024 sc0

; __device__ __forceinline__ unsigned xb_add(unsigned* p, unsigned v) { return __hip_atomic_fetch_add(p, v, __ATOMIC_RELAXED, __HIP_MEMORY_SCOPE_AGENT); }
; __device__ __forceinline__ void xcd_barrier(const XcdBarrier& b) {
;     ...
;             __builtin_amdgcn_fence(__ATOMIC_ACQUIRE, "agent");
;             xb_add(&bar[XB_XGEN(b.x)], 1u);
;             asm volatile("s_waitcnt vmcnt(0)" ::: "memory");
.LBB0_551:
	s_or_b64 exec, exec, s[6:7]
	s_mov_b64 s[6:7], exec
	v_mbcnt_lo_u32_b32 v2, s6, 0
	v_mbcnt_hi_u32_b32 v2, s7, v2
	v_cmp_eq_u32_e32 vcc, 0, v2
	s_waitcnt vmcnt(0)
	s_and_saveexec_b64 s[10:11], vcc
	s_cbranch_execz .LBB0_553
	s_bcnt1_i32_b64 s0, s[6:7]
	v_mov_b32_e32 v2, s0
	v_mov_b32_e32 v3, 0x2000
	global_atomic_add v3, v2, s[8:9] offset:1024

; __device__ __forceinline__ unsigned xb_add(unsigned* p, unsigned v) { return __hip_atomic_fetch_add(p, v, __ATOMIC_RELAXED, __HIP_MEMORY_SCOPE_AGENT); }
; __device__ __forceinline__ void xcd_barrier(const XcdBarrier& b) {
;     ...
;     if (threadIdx.x == 0) {
;         unsigned* bar = b.bar;
;         __builtin_amdgcn_s_waitcnt(0);
;         unsigned nloc = b.st[0], nx = b.st[1];
;         if (nloc == 0u) { xcd_barrier_complete(bar, b.x, nloc, nx); b.st[0] = nloc; b.st[1] = nx; }
;         const unsigned old = xb_add(&bar[XB_XSUB(b.x)], 1u);
;         const unsigned gen = old / nloc;
;         if (old + 1u == (gen + 1u) * nloc) {
;             __builtin_amdgcn_fence(__ATOMIC_RELEASE, "agent");
;             asm volatile("s_waitcnt vmcnt(0)" ::: "memory");
;             const unsigned og = xb_add(&bar[XB_TOP], 1u);
;             const unsigned tg = og / nx;
;             if (og + 1u == (tg + 1u) * nx) xb_add(&bar[XB_TOPGEN], 1u);
.LBB0_635:
	s_andn2_saveexec_b64 s[2:3], s[10:11]
	s_cbranch_execz .LBB0_655
	s_mov_b64 s[10:11], exec
	buffer_inv sc1
	s_waitcnt lgkmcnt(0)
	v_mov_b32_e32 v3, 0x20188
	ds_read_b32 v3, v3
	s_waitcnt lgkmcnt(0)
	v_readfirstlane_b32 s0, v3
	s_cmp_lg_u32 s0, 0
	s_cbranch_scc1 .Lxloc_out
	buffer_wbl2 sc1
	s_waitcnt lgkmcnt(0)
	s_waitcnt vmcnt(0)
	v_mbcnt_lo_u32_b32 v3, s10, 0
	v_mbcnt_hi_u32_b32 v3, s11, v3
	v_cmp_eq_u32_e32 vcc, 0, v3
	s_and_saveexec_b64 s[12:13], vcc
	s_cbranch_execz .LBB0_638
	s_bcnt1_i32_b64 s0, s[10:11]
	v_mov_b32_e32 v4, s0
	v_mov_b32_e32 v5, 0x7000
	global_atomic_add v4, v5, v4, s[6:7] offset:1024 sc0

; __device__ __forceinline__ unsigned xb_add(unsigned* p, unsigned v) { return __hip_atomic_fetch_add(p, v, __ATOMIC_RELAXED, __HIP_MEMORY_SCOPE_AGENT); }
; __device__ __forceinline__ void xcd_barrier(const XcdBarrier& b) {
;     ...
;             __builtin_amdgcn_fence(__ATOMIC_ACQUIRE, "agent");
;             xb_add(&bar[XB_XGEN(b.x)], 1u);
;             asm volatile("s_waitcnt vmcnt(0)" ::: "memory");
.Lxloc_out:
	s_mov_b64 s[6:7], exec
	v_mbcnt_lo_u32_b32 v2, s6, 0
	v_mbcnt_hi_u32_b32 v2, s7, v2
	v_cmp_eq_u32_e32 vcc, 0, v2
	s_waitcnt vmcnt(0)
	s_and_saveexec_b64 s[10:11], vcc
	s_cbranch_execz .LBB0_654
	s_bcnt1_i32_b64 s0, s[6:7]
	v_mov_b32_e32 v2, s0
	v_mov_b32_e32 v3, 0x2000
	global_atomic_add v3, v2, s[8:9] offset:1024

; __device__ __forceinline__ unsigned xb_add(unsigned* p, unsigned v) { return __hip_atomic_fetch_add(p, v, __ATOMIC_RELAXED, __HIP_MEMORY_SCOPE_AGENT); }
; __device__ __forceinline__ void xcd_barrier(const XcdBarrier& b) {
;     ...
;     if (threadIdx.x == 0) {
;         unsigned* bar = b.bar;
;         __builtin_amdgcn_s_waitcnt(0);
;         unsigned nloc = b.st[0], nx = b.st[1];
;         if (nloc == 0u) { xcd_barrier_complete(bar, b.x, nloc, nx); b.st[0] = nloc; b.st[1] = nx; }
;         const unsigned old = xb_add(&bar[XB_XSUB(b.x)], 1u);
;         const unsigned gen = old / nloc;
;         if (old + 1u == (gen + 1u) * nloc) {
;             __builtin_amdgcn_fence(__ATOMIC_RELEASE, "agent");
;             asm volatile("s_waitcnt vmcnt(0)" ::: "memory");
;             const unsigned og = xb_add(&bar[XB_TOP], 1u);
;             const unsigned tg = og / nx;
;             if (og + 1u == (tg + 1u) * nx) xb_add(&bar[XB_TOPGEN], 1u);
.LBB0_718:
	s_andn2_saveexec_b64 s[2:3], s[10:11]
	s_cbranch_execz .LBB0_738
	s_mov_b64 s[10:11], exec
	buffer_inv sc1
	s_waitcnt lgkmcnt(0)
	v_mov_b32_e32 v3, 0x20188
	ds_read_b32 v3, v3
	s_waitcnt lgkmcnt(0)
	v_readfirstlane_b32 s1, v3
	s_cmp_lg_u32 s1, 0
	s_cbranch_scc1 .Lxloc_up
	buffer_wbl2 sc1
	s_waitcnt lgkmcnt(0)
	s_waitcnt vmcnt(0)
	v_mbcnt_lo_u32_b32 v3, s10, 0
	v_mbcnt_hi_u32_b32 v3, s11, v3
	v_cmp_eq_u32_e32 vcc, 0, v3
	s_and_saveexec_b64 s[12:13], vcc
	s_cbranch_execz .LBB0_721
	s_bcnt1_i32_b64 s1, s[10:11]
	v_mov_b32_e32 v4, s1
	v_mov_b32_e32 v5, 0x7000
	global_atomic_add v4, v5, v4, s[6:7] offset:1024 sc0

; __device__ __forceinline__ unsigned xb_add(unsigned* p, unsigned v) { return __hip_atomic_fetch_add(p, v, __ATOMIC_RELAXED, __HIP_MEMORY_SCOPE_AGENT); }
; __device__ __forceinline__ void xcd_barrier(const XcdBarrier& b) {
;     ...
;             __builtin_amdgcn_fence(__ATOMIC_ACQUIRE, "agent");
;             xb_add(&bar[XB_XGEN(b.x)], 1u);
;             asm volatile("s_waitcnt vmcnt(0)" ::: "memory");
.Lxloc_up:
	s_mov_b64 s[6:7], exec
	v_mbcnt_lo_u32_b32 v2, s6, 0
	v_mbcnt_hi_u32_b32 v2, s7, v2
	v_cmp_eq_u32_e32 vcc, 0, v2
	s_waitcnt vmcnt(0)
	s_and_saveexec_b64 s[10:11], vcc
	s_cbranch_execz .LBB0_737
	s_bcnt1_i32_b64 s1, s[6:7]
	v_mov_b32_e32 v2, s1
	v_mov_b32_e32 v3, 0x2000
	global_atomic_add v3, v2, s[8:9] offset:1024

; __device__ __forceinline__ unsigned xb_ld(unsigned* p)              { return __hip_atomic_load(p, __ATOMIC_RELAXED, __HIP_MEMORY_SCOPE_AGENT); }
; __device__ __forceinline__ unsigned xb_add(unsigned* p, unsigned v) { return __hip_atomic_fetch_add(p, v, __ATOMIC_RELAXED, __HIP_MEMORY_SCOPE_AGENT); }
; #define XB_SPIN(cond, bar) do { unsigned _sp = 0; while (cond) { __builtin_amdgcn_s_sleep(1); \
;     if ((++_sp & 255u) == 0u) { if (xb_ld(&(bar)[XB_TMO])) break; if (_sp > XB_SPIN_CAP) { atomicAdd(&(bar)[XB_TMO], 1u); break; } } } } while (0)
; __device__ __forceinline__ void xcd_barrier(const XcdBarrier& b) {
;     ...
;         const unsigned old = xb_add(&bar[XB_XSUB(b.x)], 1u);
;         const unsigned gen = old / nloc;
;         if (old + 1u == (gen + 1u) * nloc) {
;             __builtin_amdgcn_fence(__ATOMIC_RELEASE, "agent");
;             asm volatile("s_waitcnt vmcnt(0)" ::: "memory");
;             const unsigned og = xb_add(&bar[XB_TOP], 1u);
;             const unsigned tg = og / nx;
;             if (og + 1u == (tg + 1u) * nx) xb_add(&bar[XB_TOPGEN], 1u);
;             else XB_SPIN(xb_ld(&bar[XB_TOPGEN]) == tg, bar);
;             __builtin_amdgcn_fence(__ATOMIC_ACQUIRE, "agent");
;             xb_add(&bar[XB_XGEN(b.x)], 1u);
;             asm volatile("s_waitcnt vmcnt(0)" ::: "memory");
;         } else {
;             XB_SPIN(xb_ld(&bar[XB_XGEN(b.x)]) == gen, bar);
.LBB0_803:
	s_or_b64 exec, exec, s[10:11]
	v_cvt_f32_u32_e32 v6, v4
	s_waitcnt vmcnt(0)
	v_readfirstlane_b32 s0, v5
	v_sub_u32_e32 v5, 0, v4
	v_rcp_iflag_f32_e32 v6, v6
	v_add_u32_e32 v7, s0, v3
	v_mul_f32_e32 v6, 0x4f7ffffe, v6
	v_cvt_u32_f32_e32 v6, v6
	v_mul_lo_u32 v3, v5, v6
	v_mul_hi_u32 v3, v6, v3
	v_add_u32_e32 v3, v6, v3
	v_mul_hi_u32 v3, v7, v3
	v_mul_lo_u32 v5, v3, v4
	v_sub_u32_e32 v5, v7, v5
	v_add_u32_e32 v6, 1, v3
	v_cmp_ge_u32_e32 vcc, v5, v4
	s_nop 1
	v_cndmask_b32_e32 v3, v3, v6, vcc
	v_sub_u32_e32 v6, v5, v4
	v_cndmask_b32_e32 v5, v5, v6, vcc
	v_add_u32_e32 v6, 1, v3
	v_cmp_ge_u32_e32 vcc, v5, v4
	v_add_u32_e32 v5, 1, v7
	s_nop 0
	v_cndmask_b32_e32 v3, v3, v6, vcc
	v_mul_lo_u32 v6, v4, v3
	v_add_u32_e32 v4, v6, v4
	v_cmp_ne_u32_e32 vcc, v5, v4
	s_and_saveexec_b64 s[0:1], vcc
	s_xor_b64 s[8:9], exec, s[0:1]
	s_cbranch_execz .LBB0_817
	buffer_inv sc1
	s_waitcnt lgkmcnt(0)
	v_mov_b32_e32 v2, 0x2000
	global_load_dword v2, v2, s[6:7] offset:1024 sc1
	s_add_u32 s14, s6, 0x2400
	s_addc_u32 s15, s7, 0
	s_waitcnt vmcnt(0)
	v_cmp_eq_u32_e32 vcc, v2, v3
	s_and_saveexec_b64 s[10:11], vcc
	s_cbranch_execz .LBB0_816
	s_add_u32 s12, s4, 0x4200
	s_addc_u32 s13, s5, 0
	s_mov_b32 s0, 1
	s_mov_b64 s[16:17], 0
	s_branch .LBB0_807

; __device__ __forceinline__ unsigned xb_add(unsigned* p, unsigned v) { return __hip_atomic_fetch_add(p, v, __ATOMIC_RELAXED, __HIP_MEMORY_SCOPE_AGENT); }
; __device__ __forceinline__ void xcd_barrier(const XcdBarrier& b) {
;     ...
;     if (threadIdx.x == 0) {
;         unsigned* bar = b.bar;
;         __builtin_amdgcn_s_waitcnt(0);
;         unsigned nloc = b.st[0], nx = b.st[1];
;         if (nloc == 0u) { xcd_barrier_complete(bar, b.x, nloc, nx); b.st[0] = nloc; b.st[1] = nx; }
;         const unsigned old = xb_add(&bar[XB_XSUB(b.x)], 1u);
;         const unsigned gen = old / nloc;
;         if (old + 1u == (gen + 1u) * nloc) {
;             __builtin_amdgcn_fence(__ATOMIC_RELEASE, "agent");
;             asm volatile("s_waitcnt vmcnt(0)" ::: "memory");
;             const unsigned og = xb_add(&bar[XB_TOP], 1u);
;             const unsigned tg = og / nx;
;             if (og + 1u == (tg + 1u) * nx) xb_add(&bar[XB_TOPGEN], 1u);
.LBB0_817:
	s_andn2_saveexec_b64 s[0:1], s[8:9]
	s_cbranch_execz .LBB0_268
	s_mov_b64 s[8:9], exec
	buffer_inv sc1
	s_waitcnt lgkmcnt(0)
	v_mov_b32_e32 v3, 0x20188
	ds_read_b32 v3, v3
	s_waitcnt lgkmcnt(0)
	v_readfirstlane_b32 s0, v3
	s_cmp_lg_u32 s0, 0
	s_cselect_b32 s0, 1, 0
	s_cmp_eq_u32 s71, 0
	s_cselect_b32 s0, s0, 0
	s_cmp_lg_u32 s0, 0
	s_cbranch_scc1 .Lxloc_down
	buffer_wbl2 sc1
	s_waitcnt lgkmcnt(0)
	s_waitcnt vmcnt(0)
	v_mbcnt_lo_u32_b32 v3, s8, 0
	v_mbcnt_hi_u32_b32 v3, s9, v3
	v_cmp_eq_u32_e32 vcc, 0, v3
	s_and_saveexec_b64 s[10:11], vcc
	s_cbranch_execz .LBB0_820
	s_bcnt1_i32_b64 s0, s[8:9]
	v_mov_b32_e32 v4, s0
	v_mov_b32_e32 v5, 0x7000
	global_atomic_add v4, v5, v4, s[4:5] offset:1024 sc0

; __device__ __forceinline__ unsigned xb_add(unsigned* p, unsigned v) { return __hip_atomic_fetch_add(p, v, __ATOMIC_RELAXED, __HIP_MEMORY_SCOPE_AGENT); }
; __device__ __forceinline__ void xcd_barrier(const XcdBarrier& b) {
;     ...
;             __builtin_amdgcn_fence(__ATOMIC_ACQUIRE, "agent");
;             xb_add(&bar[XB_XGEN(b.x)], 1u);
;             asm volatile("s_waitcnt vmcnt(0)" ::: "memory");
.Lxloc_down:
	s_mov_b64 s[4:5], exec
	v_mbcnt_lo_u32_b32 v2, s4, 0
	v_mbcnt_hi_u32_b32 v2, s5, v2
	v_cmp_eq_u32_e32 vcc, 0, v2
	s_waitcnt vmcnt(0)
	s_and_saveexec_b64 s[8:9], vcc
	s_cbranch_execz .LBB0_267
	s_bcnt1_i32_b64 s0, s[4:5]
	v_mov_b32_e32 v2, s0
	v_mov_b32_e32 v3, 0x2000
	global_atomic_add v3, v2, s[6:7] offset:1024
	s_branch .LBB0_267
